# hbkeep13: a 13th h block kept in LDS [0x22000,0x23c00) for waves 0-6 (wave 7 still re-loads it)
# baseline (speedup 1.0000x reference)
; __device__ __forceinline__ unsigned cvtpk(float lo, float hi) { f32x2 v = {lo, hi}; bf16x2_t b = __builtin_convertvector(v, bf16x2_t); return __builtin_bit_cast(unsigned, b); }
;     __device__ __forceinline__ void operator()(const Acc& acc, const Unit& u, int wr, int wc, int fr, int fq) const {
;     ...
;                 for (int bj = 0; bj < 2; ++bj) {
;                     const size_t off = (size_t)row * DM + colbase + 32 * bj;
;                     const f32x4 h0 = xv[m][bj][0] + acc[ai][bj][m][0], h1 = xv[m][bj][1] + acc[ai][bj][m][1];
;                     u32x4 w; w.x = cvtpk(h0.x, h0.y); w.y = cvtpk(h0.z, h0.w); w.z = cvtpk(h1.x, h1.y); w.w = cvtpk(h1.z, h1.w);
;                     *(u32x4*)(HB + off) = w;
;                     ss += (h0.x * h0.x + h0.y * h0.y) + (h0.z * h0.z + h0.w * h0.w) + (h1.x * h1.x + h1.y * h1.y) + (h1.z * h1.z + h1.w * h1.w);
;                 }
;                 ss = quad_sum(ss);
;                 if (fq == 0) atomicAdd(rowss + row, ss);
.LBB0_737:
	s_or_b64 exec, exec, s[20:21]
	v_lshlrev_b64 v[32:33], 12, v[116:117]
	v_pk_add_f32 v[30:31], v[30:31], v[94:95]
	v_pk_add_f32 v[28:29], v[28:29], v[92:93]
	v_pk_add_f32 v[34:35], v[26:27], v[90:91]
	v_pk_add_f32 v[36:37], v[24:25], v[88:89]
	v_lshl_add_u64 v[32:33], s[10:11], 0, v[32:33]
	v_cvt_pk_bf16_f32 v24, v28, v29
	v_cvt_pk_bf16_f32 v25, v30, v31
	v_cvt_pk_bf16_f32 v26, v36, v37
	v_cvt_pk_bf16_f32 v27, v34, v35
	v_lshl_add_u64 v[32:33], v[188:189], 1, v[32:33]
	s_cmp_eq_u32 s79, 64
	s_cbranch_scc0 .Lhbk_w
	s_cmp_eq_u32 s86, 0xc0
	s_cbranch_scc1 .Lhbk_ws
.Lhbk_w:
	v_mov_b32_e32 v206, 0x22000
	v_lshl_add_u32 v206, v200, 4, v206
	v_lshl_add_u32 v206, s79, 6, v206
	v_lshl_add_u32 v206, s86, 4, v206
	ds_write_b128 v206, v[24:27]
.Lhbk_ws:
	flat_store_dwordx4 v[32:33], v[24:27]
	v_pk_add_f32 v[20:21], v[20:21], v[84:85]
	v_pk_add_f32 v[22:23], v[22:23], v[86:87]
	v_mul_f32_e32 v24, v29, v29
	v_mul_f32_e32 v25, v31, v31
	v_fmac_f32_e32 v24, v28, v28
	v_fmac_f32_e32 v25, v30, v30
	v_add_f32_e32 v24, v24, v25
	v_mul_f32_e32 v25, v37, v37
	v_fmac_f32_e32 v25, v36, v36
	v_add_f32_e32 v24, v24, v25
	v_mul_f32_e32 v25, v35, v35
	v_fmac_f32_e32 v25, v34, v34
	v_add_f32_e32 v26, v25, v24
	v_pk_add_f32 v[24:25], v[18:19], v[82:83]
	v_pk_add_f32 v[18:19], v[16:17], v[80:81]
	v_mul_f32_e32 v17, v21, v21
	v_cvt_pk_bf16_f32 v16, v20, v21
	v_fmac_f32_e32 v17, v20, v20
	v_mul_f32_e32 v20, v23, v23
	v_fmac_f32_e32 v20, v22, v22
	v_add_f32_e32 v17, v17, v20
	v_mul_f32_e32 v20, v19, v19
	v_fmac_f32_e32 v20, v18, v18
	v_add_f32_e32 v17, v17, v20
	v_mul_f32_e32 v20, v25, v25
	v_fmac_f32_e32 v20, v24, v24
	v_add_f32_e32 v17, v20, v17
	v_add_f32_e32 v20, v26, v17
	ds_swizzle_b32 v21, v20 offset:swizzle(SWAP,16)
	v_cvt_pk_bf16_f32 v17, v22, v23
	v_cvt_pk_bf16_f32 v18, v18, v19
	v_cvt_pk_bf16_f32 v19, v24, v25
	flat_store_dwordx4 v[32:33], v[16:19] offset:64
	s_waitcnt lgkmcnt(0)
	s_nop 0
	v_add_f32_e32 v16, v20, v21
	v_mov_b32_e32 v17, v16
	s_nop 1
	v_permlane32_swap_b32_e32 v16, v17
	s_and_saveexec_b64 s[20:21], vcc
	s_cbranch_execz .LBB0_739
	v_add_f32_e32 v16, v16, v17
	flat_atomic_add_f32 v[112:113], v16 offset:640

; __device__ __forceinline__ float bflo(unsigned u) { return __uint_as_float(u << 16); }
;     __device__ __forceinline__ void operator()(const Acc& acc, const Unit& u, int wr, int wc, int fr, int fq) const {
;     ...
;             for (int m = 0; m < 4; ++m) { const int row = u.pm * 256 + ai * 128 + wr * 64 + m * 16 + fr; const size_t off = (size_t)row * DM + colbase;
;                 rsv[m] = rowss[row];
; #pragma unroll
;                 for (int bj = 0; bj < 2; ++bj) { const u32x4 hw = __builtin_nontemporal_load((const u32x4*)(hin + off + 32 * bj));
;                     hv[m][bj][0] = (f32x4){bflo(hw.x), bfhi(hw.x), bflo(hw.y), bfhi(hw.y)}; hv[m][bj][1] = (f32x4){bflo(hw.z), bfhi(hw.z), bflo(hw.w), bfhi(hw.w)};
;                     pw[m][bj] = __builtin_nontemporal_load((const u32x4*)(PP + off + 32 * bj)); } }
; #pragma unroll
;             for (int m = 0; m < 4; ++m) {
;                 const int row = u.pm * 256 + ai * 128 + wr * 64 + m * 16 + fr;
;                 const float rs = rsqrtf(rsv[m] * (1.0f / DM) + EPS) * -1.4426950408889634f;
; #pragma unroll
;                 for (int bj = 0; bj < 2; ++bj) {
;                     const size_t off = (size_t)row * DM + colbase + 32 * bj;
;                     f32x4 h0 = hv[m][bj][0], h1 = hv[m][bj][1];
;                     const u32x4 p4 = pw[m][bj];
;                     const f32x4 a0 = acc[ai][bj][m][0], a1 = acc[ai][bj][m][1];
;                     h0.x += bflo(p4.x) * __builtin_amdgcn_rcpf(1.0f + __builtin_amdgcn_exp2f(a0.x * rs));
;                     h0.y += bfhi(p4.x) * __builtin_amdgcn_rcpf(1.0f + __builtin_amdgcn_exp2f(a0.y * rs));
;                     h0.z += bflo(p4.y) * __builtin_amdgcn_rcpf(1.0f + __builtin_amdgcn_exp2f(a0.z * rs));
;                     h0.w += bfhi(p4.y) * __builtin_amdgcn_rcpf(1.0f + __builtin_amdgcn_exp2f(a0.w * rs));
;                     h1.x += bflo(p4.z) * __builtin_amdgcn_rcpf(1.0f + __builtin_amdgcn_exp2f(a1.x * rs));
;                     h1.y += bfhi(p4.z) * __builtin_amdgcn_rcpf(1.0f + __builtin_amdgcn_exp2f(a1.y * rs));
;                     h1.z += bflo(p4.w) * __builtin_amdgcn_rcpf(1.0f + __builtin_amdgcn_exp2f(a1.z * rs));
;                     h1.w += bfhi(p4.w) * __builtin_amdgcn_rcpf(1.0f + __builtin_amdgcn_exp2f(a1.w * rs));
;                     *(f32x4*)(out + off) = h0; *(f32x4*)(out + off + 4) = h1;
.LBB0_814:
	v_mov_b64_e32 v[206:207], v[224:225]
	v_mov_b64_e32 v[208:209], v[226:227]
	v_mov_b64_e32 v[172:173], v[228:229]
	v_mov_b64_e32 v[174:175], v[230:231]
	v_mov_b64_e32 v[164:165], v[232:233]
	v_mov_b64_e32 v[166:167], v[234:235]
	v_mov_b64_e32 v[156:157], v[236:237]
	v_mov_b64_e32 v[158:159], v[238:239]
	v_mov_b64_e32 v[148:149], v[240:241]
	v_mov_b64_e32 v[150:151], v[242:243]
	v_mov_b64_e32 v[140:141], v[210:211]
	v_mov_b64_e32 v[142:143], v[212:213]
	v_mov_b64_e32 v[236:237], v[218:219]
	v_mov_b64_e32 v[238:239], v[220:221]
	v_mov_b64_e32 v[240:241], v[222:223]
	v_mov_b32_e32 v128, v200
	s_lshl_b32 s11, s42, 8
	v_and_b32_e32 v129, 15, v128
	v_bfe_u32 v128, v128, 4, 2
	s_or_b32 s11, s11, s86
	s_nop 0
	v_lshl_add_u32 v188, v128, 3, s11
	s_lshl_b32 s11, s41, 8
	s_add_i32 s11, s11, s79
	v_add_u32_e32 v190, s11, v129
	v_ashrrev_i32_e32 v191, 31, v190
	v_lshl_add_u64 v[192:193], v[190:191], 2, s[80:81]
	flat_load_dword v226, v[192:193]
	v_ashrrev_i32_e32 v189, 31, v188
	v_lshlrev_b64 v[128:129], 11, v[190:191]
	v_lshl_add_u64 v[222:223], v[128:129], 0, v[188:189]
	v_lshlrev_b64 v[128:129], 1, v[222:223]
	v_lshl_add_u64 v[130:131], s[6:7], 0, v[128:129]
	v_lshl_add_u64 v[128:129], s[8:9], 0, v[128:129]
	flat_load_dwordx4 v[210:213], v[128:129] nt
	flat_load_dword v234, v[192:193] offset:64
	flat_load_dword v235, v[192:193] offset:128
	flat_load_dword v191, v[192:193] offset:192
	flat_load_dwordx4 v[218:221], v[128:129] offset:64 nt
	v_add_u32_e32 v132, 16, v190
	v_add_u32_e32 v134, 32, v190
	v_add_u32_e32 v136, 48, v190
	v_ashrrev_i32_e32 v133, 31, v132
	v_ashrrev_i32_e32 v135, 31, v134
	v_ashrrev_i32_e32 v137, 31, v136
	v_lshlrev_b64 v[132:133], 11, v[132:133]
	v_lshlrev_b64 v[134:135], 11, v[134:135]
	v_lshlrev_b64 v[136:137], 11, v[136:137]
	v_lshl_add_u64 v[198:199], v[132:133], 0, v[188:189]
	v_lshl_add_u64 v[196:197], v[134:135], 0, v[188:189]
	v_lshl_add_u64 v[194:195], v[136:137], 0, v[188:189]
	v_lshlrev_b64 v[132:133], 1, v[198:199]
	v_lshlrev_b64 v[134:135], 1, v[196:197]
	v_lshlrev_b64 v[136:137], 1, v[194:195]
	v_lshl_add_u64 v[128:129], s[6:7], 0, v[132:133]
	v_lshl_add_u64 v[130:131], s[8:9], 0, v[132:133]
	v_lshl_add_u64 v[132:133], s[6:7], 0, v[134:135]
	v_lshl_add_u64 v[134:135], s[8:9], 0, v[134:135]
	v_lshl_add_u64 v[138:139], s[6:7], 0, v[136:137]
	v_lshl_add_u64 v[224:225], s[8:9], 0, v[136:137]
	flat_load_dwordx4 v[168:171], v[130:131] nt
	flat_load_dwordx4 v[160:163], v[130:131] offset:64 nt
	flat_load_dwordx4 v[152:155], v[134:135] nt
	flat_load_dwordx4 v[144:147], v[134:135] offset:64 nt
	s_nop 0
	v_mov_b64_e32 v[132:133], v[244:245]
	v_mov_b64_e32 v[134:135], v[246:247]
	s_nop 0
	flat_load_dwordx4 v[136:139], v[224:225] nt
	flat_load_dwordx4 v[128:131], v[224:225] offset:64 nt
	s_waitcnt vmcnt(0) lgkmcnt(0)
	v_fmamk_f32 v224, v226, 0x3a000000, v205
	v_mul_f32_e32 v225, 0x4b800000, v224
	v_cmp_gt_f32_e32 vcc, s40, v224
	v_lshlrev_b32_e32 v228, 16, v208
	s_nop 0
	v_cndmask_b32_e32 v224, v224, v225, vcc
	v_rsq_f32_e32 v232, v224
	v_and_b32_e32 v229, 0xffff0000, v208
	v_lshlrev_b32_e32 v230, 16, v212
	v_and_b32_e32 v231, 0xffff0000, v212
	v_mul_f32_e32 v208, 0x45800000, v232
	v_cndmask_b32_e32 v208, v232, v208, vcc
	v_mul_f32_e32 v212, 0xbfb8aa3b, v208
	v_mul_f32_e32 v124, v124, v212
	v_mul_f32_e32 v125, v125, v212
	v_mul_f32_e32 v120, v120, v212
	v_mul_f32_e32 v121, v121, v212
	v_exp_f32_e32 v124, v124
	v_exp_f32_e32 v125, v125
	v_exp_f32_e32 v120, v120
	v_exp_f32_e32 v121, v121
	v_add_f32_e32 v124, 1.0, v124
	v_add_f32_e32 v125, 1.0, v125
	v_add_f32_e32 v208, 1.0, v120
	v_add_f32_e32 v233, 1.0, v121
	v_rcp_f32_e32 v120, v124
	v_rcp_f32_e32 v121, v125
	v_lshlrev_b32_e32 v224, 16, v206
	v_and_b32_e32 v225, 0xffff0000, v206
	v_lshlrev_b32_e32 v226, 16, v210
	v_and_b32_e32 v227, 0xffff0000, v210
	v_mul_f32_e32 v126, v126, v212
	v_mul_f32_e32 v127, v127, v212
	v_mul_f32_e32 v122, v122, v212
	v_exp_f32_e32 v126, v126
	v_exp_f32_e32 v127, v127
	v_pk_fma_f32 v[124:125], v[120:121], v[226:227], v[224:225]
	v_mul_f32_e32 v120, v123, v212
	v_exp_f32_e32 v122, v122
	v_exp_f32_e32 v123, v120
	v_mul_f32_e32 v116, v116, v212
	v_mul_f32_e32 v117, v117, v212
	v_exp_f32_e32 v116, v116
	v_exp_f32_e32 v117, v117
	v_mul_f32_e32 v118, v118, v212
	v_mul_f32_e32 v119, v119, v212
	v_add_f32_e32 v126, 1.0, v126
	v_add_f32_e32 v127, 1.0, v127
	v_exp_f32_e32 v118, v118
	v_exp_f32_e32 v119, v119
	v_mul_f32_e32 v112, v112, v212
	v_mul_f32_e32 v113, v113, v212
	v_rcp_f32_e32 v126, v126
	v_rcp_f32_e32 v127, v127
	v_add_f32_e32 v122, 1.0, v122
	v_add_f32_e32 v123, 1.0, v123
	v_exp_f32_e32 v112, v112
	v_exp_f32_e32 v113, v113
	v_rcp_f32_e32 v232, v208
	v_rcp_f32_e32 v233, v233
	v_rcp_f32_e32 v122, v122
	v_rcp_f32_e32 v123, v123
	v_add_f32_e32 v116, 1.0, v116
	v_add_f32_e32 v117, 1.0, v117
	v_lshlrev_b32_e32 v206, 16, v207
	v_and_b32_e32 v207, 0xffff0000, v207
	v_lshlrev_b32_e32 v210, 16, v211
	v_and_b32_e32 v211, 0xffff0000, v211
	v_rcp_f32_e32 v116, v116
	v_rcp_f32_e32 v117, v117
	v_add_f32_e32 v118, 1.0, v118
	v_add_f32_e32 v119, 1.0, v119
	v_pk_fma_f32 v[126:127], v[126:127], v[210:211], v[206:207]
	v_lshlrev_b32_e32 v206, 16, v209
	v_and_b32_e32 v207, 0xffff0000, v209
	v_lshlrev_b32_e32 v208, 16, v213
	v_and_b32_e32 v209, 0xffff0000, v213
	v_rcp_f32_e32 v118, v118
	v_rcp_f32_e32 v119, v119
	v_add_f32_e32 v112, 1.0, v112
	v_add_f32_e32 v113, 1.0, v113
	v_pk_fma_f32 v[120:121], v[232:233], v[230:231], v[228:229]
	v_pk_fma_f32 v[122:123], v[122:123], v[208:209], v[206:207]
	v_lshl_add_u64 v[206:207], v[222:223], 2, s[2:3]
	v_rcp_f32_e32 v112, v112
	v_rcp_f32_e32 v113, v113
	flat_store_dwordx4 v[206:207], v[120:123] offset:16
; __device__ __forceinline__ float bflo(unsigned u) { return __uint_as_float(u << 16); }
; __device__ __forceinline__ float bfhi(unsigned u) { return __uint_as_float(u & 0xffff0000u); }
;     __device__ __forceinline__ void operator()(const Acc& acc, const Unit& u, int wr, int wc, int fr, int fq) const {
;     ...
;             for (int m = 0; m < 4; ++m) {
;                 const int row = u.pm * 256 + ai * 128 + wr * 64 + m * 16 + fr;
;                 const float rs = rsqrtf(rsv[m] * (1.0f / DM) + EPS) * -1.4426950408889634f;
; #pragma unroll
;                 for (int bj = 0; bj < 2; ++bj) {
;                     const size_t off = (size_t)row * DM + colbase + 32 * bj;
;                     f32x4 h0 = hv[m][bj][0], h1 = hv[m][bj][1];
;                     const u32x4 p4 = pw[m][bj];
;                     const f32x4 a0 = acc[ai][bj][m][0], a1 = acc[ai][bj][m][1];
;                     h0.x += bflo(p4.x) * __builtin_amdgcn_rcpf(1.0f + __builtin_amdgcn_exp2f(a0.x * rs));
;                     h0.y += bfhi(p4.x) * __builtin_amdgcn_rcpf(1.0f + __builtin_amdgcn_exp2f(a0.y * rs));
;                     h0.z += bflo(p4.y) * __builtin_amdgcn_rcpf(1.0f + __builtin_amdgcn_exp2f(a0.z * rs));
;                     h0.w += bfhi(p4.y) * __builtin_amdgcn_rcpf(1.0f + __builtin_amdgcn_exp2f(a0.w * rs));
;                     h1.x += bflo(p4.z) * __builtin_amdgcn_rcpf(1.0f + __builtin_amdgcn_exp2f(a1.x * rs));
;                     h1.y += bfhi(p4.z) * __builtin_amdgcn_rcpf(1.0f + __builtin_amdgcn_exp2f(a1.y * rs));
;                     h1.z += bflo(p4.w) * __builtin_amdgcn_rcpf(1.0f + __builtin_amdgcn_exp2f(a1.z * rs));
;                     h1.w += bfhi(p4.w) * __builtin_amdgcn_rcpf(1.0f + __builtin_amdgcn_exp2f(a1.w * rs));
;                     *(f32x4*)(out + off) = h0; *(f32x4*)(out + off + 4) = h1;
	flat_store_dwordx4 v[206:207], v[124:127]
	v_mul_f32_e32 v114, v114, v212
	v_lshlrev_b32_e32 v120, 16, v214
	v_and_b32_e32 v121, 0xffff0000, v214
	v_lshlrev_b32_e32 v122, 16, v218
	v_and_b32_e32 v123, 0xffff0000, v218
	v_pk_fma_f32 v[116:117], v[116:117], v[122:123], v[120:121]
	v_lshlrev_b32_e32 v120, 16, v215
	v_and_b32_e32 v121, 0xffff0000, v215
	v_lshlrev_b32_e32 v122, 16, v219
	v_and_b32_e32 v123, 0xffff0000, v219
	v_pk_fma_f32 v[118:119], v[118:119], v[122:123], v[120:121]
	v_lshlrev_b32_e32 v120, 16, v216
	v_and_b32_e32 v121, 0xffff0000, v216
	v_lshlrev_b32_e32 v122, 16, v220
	v_and_b32_e32 v123, 0xffff0000, v220
	v_pk_fma_f32 v[112:113], v[112:113], v[122:123], v[120:121]
	v_fmamk_f32 v123, v234, 0x3a000000, v205
	v_mul_f32_e32 v124, 0x4b800000, v123
	v_cmp_gt_f32_e32 vcc, s40, v123
	flat_store_dwordx4 v[206:207], v[116:119] offset:128
	v_mul_f32_e32 v115, v115, v212
	v_cndmask_b32_e32 v123, v123, v124, vcc
	v_rsq_f32_e32 v124, v123
	v_exp_f32_e32 v114, v114
	v_exp_f32_e32 v115, v115
	v_lshlrev_b32_e32 v120, 16, v217
	v_mul_f32_e32 v116, 0x45800000, v124
	v_cndmask_b32_e32 v116, v124, v116, vcc
	v_mul_f32_e32 v116, 0xbfb8aa3b, v116
	v_mul_f32_e32 v108, v108, v116
	v_mul_f32_e32 v109, v109, v116
	v_exp_f32_e32 v108, v108
	v_exp_f32_e32 v109, v109
	v_mul_f32_e32 v110, v110, v116
	v_mul_f32_e32 v111, v111, v116
	v_exp_f32_e32 v110, v110
	v_exp_f32_e32 v111, v111
	v_mul_f32_e32 v104, v104, v116
	v_mul_f32_e32 v105, v105, v116
	v_add_f32_e32 v114, 1.0, v114
	v_add_f32_e32 v115, 1.0, v115
	v_exp_f32_e32 v104, v104
	v_exp_f32_e32 v105, v105
	v_mul_f32_e32 v106, v106, v116
	v_mul_f32_e32 v107, v107, v116
	v_rcp_f32_e32 v114, v114
	v_rcp_f32_e32 v115, v115
	v_exp_f32_e32 v106, v106
	v_exp_f32_e32 v107, v107
	v_add_f32_e32 v108, 1.0, v108
	v_add_f32_e32 v109, 1.0, v109
	v_mul_f32_e32 v100, v100, v116
	v_mul_f32_e32 v101, v101, v116
	v_rcp_f32_e32 v108, v108
	v_rcp_f32_e32 v109, v109
	v_add_f32_e32 v110, 1.0, v110
	v_add_f32_e32 v111, 1.0, v111
	v_exp_f32_e32 v100, v100
	v_exp_f32_e32 v101, v101
	v_mul_f32_e32 v102, v102, v116
	v_mul_f32_e32 v103, v103, v116
	v_and_b32_e32 v121, 0xffff0000, v217
	v_lshlrev_b32_e32 v122, 16, v221
	v_and_b32_e32 v123, 0xffff0000, v221
	v_rcp_f32_e32 v110, v110
	v_rcp_f32_e32 v111, v111
	v_add_f32_e32 v104, 1.0, v104
	v_add_f32_e32 v105, 1.0, v105
	v_exp_f32_e32 v102, v102
	v_exp_f32_e32 v103, v103
	v_mul_f32_e32 v96, v96, v116
	v_mul_f32_e32 v97, v97, v116
	v_pk_fma_f32 v[114:115], v[114:115], v[122:123], v[120:121]
	v_rcp_f32_e32 v104, v104
	v_rcp_f32_e32 v105, v105
	v_add_f32_e32 v106, 1.0, v106
	v_add_f32_e32 v107, 1.0, v107
	v_exp_f32_e32 v96, v96
	v_exp_f32_e32 v97, v97
	flat_store_dwordx4 v[206:207], v[112:115] offset:144
	v_rcp_f32_e32 v106, v106
	v_rcp_f32_e32 v107, v107
	v_lshlrev_b32_e32 v112, 16, v172
	v_and_b32_e32 v113, 0xffff0000, v172
	v_lshlrev_b32_e32 v114, 16, v168
	v_and_b32_e32 v115, 0xffff0000, v168
	v_pk_fma_f32 v[108:109], v[108:109], v[114:115], v[112:113]
	v_lshlrev_b32_e32 v112, 16, v173
	v_and_b32_e32 v113, 0xffff0000, v173
	v_lshlrev_b32_e32 v114, 16, v169
	v_and_b32_e32 v115, 0xffff0000, v169
	v_add_f32_e32 v100, 1.0, v100
	v_add_f32_e32 v101, 1.0, v101
	v_pk_fma_f32 v[110:111], v[110:111], v[114:115], v[112:113]
	v_lshlrev_b32_e32 v112, 16, v174
	v_and_b32_e32 v113, 0xffff0000, v174
	v_lshlrev_b32_e32 v114, 16, v170
	v_and_b32_e32 v115, 0xffff0000, v170
	v_rcp_f32_e32 v100, v100
	v_rcp_f32_e32 v101, v101
	v_add_f32_e32 v102, 1.0, v102
	v_add_f32_e32 v103, 1.0, v103
	v_pk_fma_f32 v[104:105], v[104:105], v[114:115], v[112:113]
	v_lshlrev_b32_e32 v112, 16, v175
	v_and_b32_e32 v113, 0xffff0000, v175
	v_lshlrev_b32_e32 v114, 16, v171
	v_and_b32_e32 v115, 0xffff0000, v171
	v_rcp_f32_e32 v102, v102
	v_rcp_f32_e32 v103, v103
	v_add_f32_e32 v96, 1.0, v96
	v_add_f32_e32 v97, 1.0, v97
	v_pk_fma_f32 v[106:107], v[106:107], v[114:115], v[112:113]
	v_lshl_add_u64 v[112:113], v[198:199], 2, s[2:3]
	v_rcp_f32_e32 v96, v96
	v_rcp_f32_e32 v97, v97
	flat_store_dwordx4 v[112:113], v[104:107] offset:16
	flat_store_dwordx4 v[112:113], v[108:111]
	v_mul_f32_e32 v98, v98, v116
	v_lshlrev_b32_e32 v104, 16, v164
	v_and_b32_e32 v105, 0xffff0000, v164
	v_lshlrev_b32_e32 v106, 16, v160
	v_and_b32_e32 v107, 0xffff0000, v160
	v_pk_fma_f32 v[100:101], v[100:101], v[106:107], v[104:105]
	v_lshlrev_b32_e32 v104, 16, v165
	v_and_b32_e32 v105, 0xffff0000, v165
	v_lshlrev_b32_e32 v106, 16, v161
	v_and_b32_e32 v107, 0xffff0000, v161
	v_pk_fma_f32 v[102:103], v[102:103], v[106:107], v[104:105]
	v_lshlrev_b32_e32 v104, 16, v166
	v_and_b32_e32 v105, 0xffff0000, v166
	v_lshlrev_b32_e32 v106, 16, v162
	v_and_b32_e32 v107, 0xffff0000, v162
	v_pk_fma_f32 v[96:97], v[96:97], v[106:107], v[104:105]
	v_fmamk_f32 v107, v235, 0x3a000000, v205
	v_mul_f32_e32 v108, 0x4b800000, v107
	v_cmp_gt_f32_e32 vcc, s40, v107
	flat_store_dwordx4 v[112:113], v[100:103] offset:128
	v_mul_f32_e32 v99, v99, v116
	v_cndmask_b32_e32 v107, v107, v108, vcc
	v_rsq_f32_e32 v108, v107
	v_exp_f32_e32 v98, v98
	v_exp_f32_e32 v99, v99
	v_lshlrev_b32_e32 v104, 16, v167
	v_mul_f32_e32 v100, 0x45800000, v108
	v_cndmask_b32_e32 v100, v108, v100, vcc
	v_mul_f32_e32 v100, 0xbfb8aa3b, v100
	v_mul_f32_e32 v92, v92, v100
	v_mul_f32_e32 v93, v93, v100
	v_exp_f32_e32 v92, v92
	v_exp_f32_e32 v93, v93
	v_mul_f32_e32 v94, v94, v100
	v_mul_f32_e32 v95, v95, v100
	v_exp_f32_e32 v94, v94
	v_exp_f32_e32 v95, v95
	v_mul_f32_e32 v88, v88, v100
	v_mul_f32_e32 v89, v89, v100
	v_add_f32_e32 v98, 1.0, v98
	v_add_f32_e32 v99, 1.0, v99
	v_exp_f32_e32 v88, v88
	v_exp_f32_e32 v89, v89
	v_mul_f32_e32 v90, v90, v100
	v_mul_f32_e32 v91, v91, v100
	v_rcp_f32_e32 v98, v98
; __device__ __forceinline__ float bflo(unsigned u) { return __uint_as_float(u << 16); }
; __device__ __forceinline__ float bfhi(unsigned u) { return __uint_as_float(u & 0xffff0000u); }
;     __device__ __forceinline__ void operator()(const Acc& acc, const Unit& u, int wr, int wc, int fr, int fq) const {
;     ...
;             for (int m = 0; m < 4; ++m) {
;                 const int row = u.pm * 256 + ai * 128 + wr * 64 + m * 16 + fr;
;                 const float rs = rsqrtf(rsv[m] * (1.0f / DM) + EPS) * -1.4426950408889634f;
; #pragma unroll
;                 for (int bj = 0; bj < 2; ++bj) {
;                     const size_t off = (size_t)row * DM + colbase + 32 * bj;
;                     f32x4 h0 = hv[m][bj][0], h1 = hv[m][bj][1];
;                     const u32x4 p4 = pw[m][bj];
;                     const f32x4 a0 = acc[ai][bj][m][0], a1 = acc[ai][bj][m][1];
;                     h0.x += bflo(p4.x) * __builtin_amdgcn_rcpf(1.0f + __builtin_amdgcn_exp2f(a0.x * rs));
;                     h0.y += bfhi(p4.x) * __builtin_amdgcn_rcpf(1.0f + __builtin_amdgcn_exp2f(a0.y * rs));
;                     h0.z += bflo(p4.y) * __builtin_amdgcn_rcpf(1.0f + __builtin_amdgcn_exp2f(a0.z * rs));
;                     h0.w += bfhi(p4.y) * __builtin_amdgcn_rcpf(1.0f + __builtin_amdgcn_exp2f(a0.w * rs));
;                     h1.x += bflo(p4.z) * __builtin_amdgcn_rcpf(1.0f + __builtin_amdgcn_exp2f(a1.x * rs));
;                     h1.y += bfhi(p4.z) * __builtin_amdgcn_rcpf(1.0f + __builtin_amdgcn_exp2f(a1.y * rs));
;                     h1.z += bflo(p4.w) * __builtin_amdgcn_rcpf(1.0f + __builtin_amdgcn_exp2f(a1.z * rs));
;                     h1.w += bfhi(p4.w) * __builtin_amdgcn_rcpf(1.0f + __builtin_amdgcn_exp2f(a1.w * rs));
;                     *(f32x4*)(out + off) = h0; *(f32x4*)(out + off + 4) = h1;
	v_rcp_f32_e32 v99, v99
	v_exp_f32_e32 v90, v90
	v_exp_f32_e32 v91, v91
	v_add_f32_e32 v92, 1.0, v92
	v_add_f32_e32 v93, 1.0, v93
	v_mul_f32_e32 v84, v84, v100
	v_mul_f32_e32 v85, v85, v100
	v_rcp_f32_e32 v92, v92
	v_rcp_f32_e32 v93, v93
	v_add_f32_e32 v94, 1.0, v94
	v_add_f32_e32 v95, 1.0, v95
	v_exp_f32_e32 v84, v84
	v_exp_f32_e32 v85, v85
	v_mul_f32_e32 v86, v86, v100
	v_mul_f32_e32 v87, v87, v100
	v_and_b32_e32 v105, 0xffff0000, v167
	v_lshlrev_b32_e32 v106, 16, v163
	v_and_b32_e32 v107, 0xffff0000, v163
	v_rcp_f32_e32 v94, v94
	v_rcp_f32_e32 v95, v95
	v_add_f32_e32 v88, 1.0, v88
	v_add_f32_e32 v89, 1.0, v89
	v_exp_f32_e32 v86, v86
	v_exp_f32_e32 v87, v87
	v_mul_f32_e32 v80, v80, v100
	v_mul_f32_e32 v81, v81, v100
	v_pk_fma_f32 v[98:99], v[98:99], v[106:107], v[104:105]
	v_rcp_f32_e32 v88, v88
	v_rcp_f32_e32 v89, v89
	v_add_f32_e32 v90, 1.0, v90
	v_add_f32_e32 v91, 1.0, v91
	v_exp_f32_e32 v80, v80
	v_exp_f32_e32 v81, v81
	flat_store_dwordx4 v[112:113], v[96:99] offset:144
	v_rcp_f32_e32 v90, v90
	v_rcp_f32_e32 v91, v91
	v_lshlrev_b32_e32 v96, 16, v156
	v_and_b32_e32 v97, 0xffff0000, v156
	v_lshlrev_b32_e32 v98, 16, v152
	v_and_b32_e32 v99, 0xffff0000, v152
	v_pk_fma_f32 v[92:93], v[92:93], v[98:99], v[96:97]
	v_lshlrev_b32_e32 v96, 16, v157
	v_and_b32_e32 v97, 0xffff0000, v157
	v_lshlrev_b32_e32 v98, 16, v153
	v_and_b32_e32 v99, 0xffff0000, v153
	v_add_f32_e32 v84, 1.0, v84
	v_add_f32_e32 v85, 1.0, v85
	v_pk_fma_f32 v[94:95], v[94:95], v[98:99], v[96:97]
	v_lshlrev_b32_e32 v96, 16, v158
	v_and_b32_e32 v97, 0xffff0000, v158
	v_lshlrev_b32_e32 v98, 16, v154
	v_and_b32_e32 v99, 0xffff0000, v154
	v_rcp_f32_e32 v84, v84
	v_rcp_f32_e32 v85, v85
	v_add_f32_e32 v86, 1.0, v86
	v_add_f32_e32 v87, 1.0, v87
	v_pk_fma_f32 v[88:89], v[88:89], v[98:99], v[96:97]
	v_lshlrev_b32_e32 v96, 16, v159
	v_and_b32_e32 v97, 0xffff0000, v159
	v_lshlrev_b32_e32 v98, 16, v155
	v_and_b32_e32 v99, 0xffff0000, v155
	v_rcp_f32_e32 v86, v86
	v_rcp_f32_e32 v87, v87
	v_add_f32_e32 v80, 1.0, v80
	v_add_f32_e32 v81, 1.0, v81
	v_pk_fma_f32 v[90:91], v[90:91], v[98:99], v[96:97]
	v_lshl_add_u64 v[96:97], v[196:197], 2, s[2:3]
	v_rcp_f32_e32 v80, v80
	v_rcp_f32_e32 v81, v81
	flat_store_dwordx4 v[96:97], v[88:91] offset:16
	flat_store_dwordx4 v[96:97], v[92:95]
	v_mul_f32_e32 v82, v82, v100
	v_lshlrev_b32_e32 v88, 16, v148
	v_and_b32_e32 v89, 0xffff0000, v148
	v_lshlrev_b32_e32 v90, 16, v144
	v_and_b32_e32 v91, 0xffff0000, v144
	v_pk_fma_f32 v[84:85], v[84:85], v[90:91], v[88:89]
	v_lshlrev_b32_e32 v88, 16, v149
	v_and_b32_e32 v89, 0xffff0000, v149
	v_lshlrev_b32_e32 v90, 16, v145
	v_and_b32_e32 v91, 0xffff0000, v145
	v_pk_fma_f32 v[86:87], v[86:87], v[90:91], v[88:89]
	v_lshlrev_b32_e32 v88, 16, v150
	v_and_b32_e32 v89, 0xffff0000, v150
	v_lshlrev_b32_e32 v90, 16, v146
	v_and_b32_e32 v91, 0xffff0000, v146
	v_pk_fma_f32 v[80:81], v[80:81], v[90:91], v[88:89]
	v_fmamk_f32 v91, v191, 0x3a000000, v205
	v_mul_f32_e32 v92, 0x4b800000, v91
	v_cmp_gt_f32_e32 vcc, s40, v91
	flat_store_dwordx4 v[96:97], v[84:87] offset:128
	v_mul_f32_e32 v83, v83, v100
	v_cndmask_b32_e32 v91, v91, v92, vcc
	v_rsq_f32_e32 v92, v91
	v_exp_f32_e32 v82, v82
	v_exp_f32_e32 v83, v83
	v_lshlrev_b32_e32 v88, 16, v151
	v_mul_f32_e32 v84, 0x45800000, v92
	v_cndmask_b32_e32 v84, v92, v84, vcc
	v_mul_f32_e32 v84, 0xbfb8aa3b, v84
	v_mul_f32_e32 v76, v76, v84
	v_mul_f32_e32 v77, v77, v84
	v_exp_f32_e32 v76, v76
	v_exp_f32_e32 v77, v77
	v_mul_f32_e32 v78, v78, v84
	v_mul_f32_e32 v79, v79, v84
	v_exp_f32_e32 v78, v78
	v_exp_f32_e32 v79, v79
	v_mul_f32_e32 v72, v72, v84
	v_mul_f32_e32 v73, v73, v84
	v_add_f32_e32 v82, 1.0, v82
	v_add_f32_e32 v83, 1.0, v83
	v_exp_f32_e32 v72, v72
	v_exp_f32_e32 v73, v73
	v_mul_f32_e32 v74, v74, v84
	v_mul_f32_e32 v75, v75, v84
	v_rcp_f32_e32 v82, v82
	v_rcp_f32_e32 v83, v83
	v_exp_f32_e32 v74, v74
	v_exp_f32_e32 v75, v75
	v_add_f32_e32 v76, 1.0, v76
	v_add_f32_e32 v77, 1.0, v77
	v_mul_f32_e32 v68, v68, v84
	v_mul_f32_e32 v69, v69, v84
	v_rcp_f32_e32 v76, v76
	v_rcp_f32_e32 v77, v77
	v_add_f32_e32 v78, 1.0, v78
	v_add_f32_e32 v79, 1.0, v79
	v_exp_f32_e32 v68, v68
	v_exp_f32_e32 v69, v69
	v_mul_f32_e32 v70, v70, v84
	v_mul_f32_e32 v71, v71, v84
	v_and_b32_e32 v89, 0xffff0000, v151
	v_lshlrev_b32_e32 v90, 16, v147
	v_and_b32_e32 v91, 0xffff0000, v147
	v_rcp_f32_e32 v78, v78
	v_rcp_f32_e32 v79, v79
	v_add_f32_e32 v72, 1.0, v72
	v_add_f32_e32 v73, 1.0, v73
	v_exp_f32_e32 v70, v70
	v_exp_f32_e32 v71, v71
	v_mul_f32_e32 v64, v64, v84
	v_mul_f32_e32 v65, v65, v84
	v_pk_fma_f32 v[82:83], v[82:83], v[90:91], v[88:89]
	v_rcp_f32_e32 v72, v72
	v_rcp_f32_e32 v73, v73
	v_add_f32_e32 v74, 1.0, v74
	v_add_f32_e32 v75, 1.0, v75
	v_exp_f32_e32 v64, v64
	v_exp_f32_e32 v65, v65
	v_mul_f32_e32 v66, v66, v84
	v_mul_f32_e32 v67, v67, v84
	flat_store_dwordx4 v[96:97], v[80:83] offset:144
	v_rcp_f32_e32 v74, v74
	v_rcp_f32_e32 v75, v75
	v_lshlrev_b32_e32 v80, 16, v140
	v_and_b32_e32 v81, 0xffff0000, v140
	v_lshlrev_b32_e32 v82, 16, v136
	v_and_b32_e32 v83, 0xffff0000, v136
	v_exp_f32_e32 v66, v66
	v_exp_f32_e32 v67, v67
	v_pk_fma_f32 v[76:77], v[76:77], v[82:83], v[80:81]
	v_lshlrev_b32_e32 v80, 16, v141
	v_and_b32_e32 v81, 0xffff0000, v141
	v_lshlrev_b32_e32 v82, 16, v137
	v_and_b32_e32 v83, 0xffff0000, v137
	v_add_f32_e32 v68, 1.0, v68
	v_add_f32_e32 v69, 1.0, v69
	v_pk_fma_f32 v[78:79], v[78:79], v[82:83], v[80:81]
	v_lshlrev_b32_e32 v80, 16, v142
	v_and_b32_e32 v81, 0xffff0000, v142
	v_lshlrev_b32_e32 v82, 16, v138
	v_and_b32_e32 v83, 0xffff0000, v138
	v_rcp_f32_e32 v68, v68
	v_rcp_f32_e32 v69, v69
	v_add_f32_e32 v70, 1.0, v70
	v_add_f32_e32 v71, 1.0, v71
	v_pk_fma_f32 v[72:73], v[72:73], v[82:83], v[80:81]
; __device__ __forceinline__ float bflo(unsigned u) { return __uint_as_float(u << 16); }
;     __device__ __forceinline__ void operator()(const Acc& acc, const Unit& u, int wr, int wc, int fr, int fq) const {
;     ...
;             for (int m = 0; m < 4; ++m) { const int row = u.pm * 256 + ai * 128 + wr * 64 + m * 16 + fr; const size_t off = (size_t)row * DM + colbase;
;                 rsv[m] = rowss[row];
; #pragma unroll
;                 for (int bj = 0; bj < 2; ++bj) { const u32x4 hw = __builtin_nontemporal_load((const u32x4*)(hin + off + 32 * bj));
;                     hv[m][bj][0] = (f32x4){bflo(hw.x), bfhi(hw.x), bflo(hw.y), bfhi(hw.y)}; hv[m][bj][1] = (f32x4){bflo(hw.z), bfhi(hw.z), bflo(hw.w), bfhi(hw.w)};
;                     pw[m][bj] = __builtin_nontemporal_load((const u32x4*)(PP + off + 32 * bj)); } }
; #pragma unroll
;             for (int m = 0; m < 4; ++m) {
;                 const int row = u.pm * 256 + ai * 128 + wr * 64 + m * 16 + fr;
;                 const float rs = rsqrtf(rsv[m] * (1.0f / DM) + EPS) * -1.4426950408889634f;
; #pragma unroll
;                 for (int bj = 0; bj < 2; ++bj) {
;                     const size_t off = (size_t)row * DM + colbase + 32 * bj;
;                     f32x4 h0 = hv[m][bj][0], h1 = hv[m][bj][1];
;                     const u32x4 p4 = pw[m][bj];
;                     const f32x4 a0 = acc[ai][bj][m][0], a1 = acc[ai][bj][m][1];
;                     h0.x += bflo(p4.x) * __builtin_amdgcn_rcpf(1.0f + __builtin_amdgcn_exp2f(a0.x * rs));
;                     h0.y += bfhi(p4.x) * __builtin_amdgcn_rcpf(1.0f + __builtin_amdgcn_exp2f(a0.y * rs));
;                     h0.z += bflo(p4.y) * __builtin_amdgcn_rcpf(1.0f + __builtin_amdgcn_exp2f(a0.z * rs));
;                     h0.w += bfhi(p4.y) * __builtin_amdgcn_rcpf(1.0f + __builtin_amdgcn_exp2f(a0.w * rs));
;                     h1.x += bflo(p4.z) * __builtin_amdgcn_rcpf(1.0f + __builtin_amdgcn_exp2f(a1.x * rs));
;                     h1.y += bfhi(p4.z) * __builtin_amdgcn_rcpf(1.0f + __builtin_amdgcn_exp2f(a1.y * rs));
;                     h1.z += bflo(p4.w) * __builtin_amdgcn_rcpf(1.0f + __builtin_amdgcn_exp2f(a1.z * rs));
;                     h1.w += bfhi(p4.w) * __builtin_amdgcn_rcpf(1.0f + __builtin_amdgcn_exp2f(a1.w * rs));
;                     *(f32x4*)(out + off) = h0; *(f32x4*)(out + off + 4) = h1;
	v_lshlrev_b32_e32 v80, 16, v143
	v_and_b32_e32 v81, 0xffff0000, v143
	v_lshlrev_b32_e32 v82, 16, v139
	v_and_b32_e32 v83, 0xffff0000, v139
	v_rcp_f32_e32 v70, v70
	v_rcp_f32_e32 v71, v71
	v_add_f32_e32 v64, 1.0, v64
	v_add_f32_e32 v65, 1.0, v65
	v_pk_fma_f32 v[74:75], v[74:75], v[82:83], v[80:81]
	v_lshl_add_u64 v[80:81], v[194:195], 2, s[2:3]
	v_rcp_f32_e32 v64, v64
	v_rcp_f32_e32 v65, v65
	v_add_f32_e32 v66, 1.0, v66
	v_add_f32_e32 v67, 1.0, v67
	flat_store_dwordx4 v[80:81], v[72:75] offset:16
	v_rcp_f32_e32 v66, v66
	v_rcp_f32_e32 v67, v67
	v_lshlrev_b32_e32 v72, 16, v132
	v_and_b32_e32 v73, 0xffff0000, v132
	v_lshlrev_b32_e32 v74, 16, v128
	v_and_b32_e32 v75, 0xffff0000, v128
	v_pk_fma_f32 v[68:69], v[68:69], v[74:75], v[72:73]
	v_lshlrev_b32_e32 v72, 16, v133
	v_and_b32_e32 v73, 0xffff0000, v133
	v_lshlrev_b32_e32 v74, 16, v129
	v_and_b32_e32 v75, 0xffff0000, v129
	v_pk_fma_f32 v[70:71], v[70:71], v[74:75], v[72:73]
	v_lshlrev_b32_e32 v72, 16, v134
	v_and_b32_e32 v73, 0xffff0000, v134
	v_lshlrev_b32_e32 v74, 16, v130
	v_and_b32_e32 v75, 0xffff0000, v130
	v_pk_fma_f32 v[64:65], v[64:65], v[74:75], v[72:73]
	v_lshlrev_b32_e32 v72, 16, v135
	v_and_b32_e32 v73, 0xffff0000, v135
	v_lshlrev_b32_e32 v74, 16, v131
	v_and_b32_e32 v75, 0xffff0000, v131
	flat_store_dwordx4 v[80:81], v[76:79]
	v_pk_fma_f32 v[66:67], v[66:67], v[74:75], v[72:73]
	flat_store_dwordx4 v[80:81], v[68:71] offset:128
	flat_store_dwordx4 v[80:81], v[64:67] offset:144
	flat_load_dword v68, v[192:193] offset:512
	s_nop 0
	v_add_u32_e32 v64, 0x80, v190
	v_ashrrev_i32_e32 v65, 31, v64
	v_lshlrev_b64 v[64:65], 11, v[64:65]
	v_lshl_add_u64 v[136:137], v[64:65], 0, v[188:189]
	v_lshlrev_b64 v[64:65], 1, v[136:137]
	v_lshl_add_u64 v[66:67], s[6:7], 0, v[64:65]
	v_lshl_add_u64 v[64:65], s[8:9], 0, v[64:65]
	v_mov_b64_e32 v[124:125], v[248:249]
	v_mov_b64_e32 v[126:127], v[252:253]
	flat_load_dwordx4 v[128:131], v[64:65] nt
	v_mov_b64_e32 v[132:133], v[236:237]
	v_mov_b64_e32 v[134:135], v[238:239]
	flat_load_dwordx4 v[112:115], v[64:65] offset:64 nt
	v_add_u32_e32 v64, 0x90, v190
	v_ashrrev_i32_e32 v65, 31, v64
	v_lshlrev_b64 v[64:65], 11, v[64:65]
	v_lshl_add_u64 v[120:121], v[64:65], 0, v[188:189]
	v_lshlrev_b64 v[64:65], 1, v[120:121]
	v_lshl_add_u64 v[66:67], s[6:7], 0, v[64:65]
	v_lshl_add_u64 v[64:65], s[8:9], 0, v[64:65]
	v_mov_b64_e32 v[108:109], v[240:241]
	v_mov_b64_e32 v[110:111], v[250:251]
	v_mov_b32_e32 v100, 0x20000
	v_lshl_add_u32 v100, v200, 4, v100
	v_lshl_add_u32 v100, s79, 6, v100
	v_lshl_add_u32 v100, s86, 4, v100
	ds_read_b128 v[100:103], v100
	flat_load_dwordx4 v[104:107], v[64:65] nt
	flat_load_dwordx4 v[96:99], v[64:65] offset:64 nt
	v_add_u32_e32 v64, 0xa0, v190
	v_ashrrev_i32_e32 v65, 31, v64
	v_lshlrev_b64 v[64:65], 11, v[64:65]
	v_lshl_add_u64 v[118:119], v[64:65], 0, v[188:189]
	v_lshlrev_b64 v[64:65], 1, v[118:119]
	v_lshl_add_u64 v[66:67], s[6:7], 0, v[64:65]
	v_lshl_add_u64 v[64:65], s[8:9], 0, v[64:65]
	s_cmp_eq_u32 s79, 64
	s_cbranch_scc0 .Lhbk_r
	s_cmp_eq_u32 s86, 0xc0
	s_cbranch_scc1 .Lhbk_rl
.Lhbk_r:
	v_mov_b32_e32 v92, 0x22000
	v_lshl_add_u32 v92, v200, 4, v92
	v_lshl_add_u32 v92, s79, 6, v92
	v_lshl_add_u32 v92, s86, 4, v92
	ds_read_b128 v[92:95], v92
	s_branch .Lhbk_rd
.Lhbk_rl:
	flat_load_dwordx4 v[92:95], v[66:67] nt
.Lhbk_rd:
	flat_load_dwordx4 v[84:87], v[66:67] offset:64 nt
	flat_load_dwordx4 v[88:91], v[64:65] nt
	flat_load_dwordx4 v[80:83], v[64:65] offset:64 nt
	flat_load_dword v123, v[192:193] offset:576
	flat_load_dword v142, v[192:193] offset:640
	flat_load_dword v122, v[192:193] offset:704
	v_add_u32_e32 v64, 0xb0, v190
	v_ashrrev_i32_e32 v65, 31, v64
	v_lshlrev_b64 v[64:65], 11, v[64:65]
	v_lshl_add_u64 v[116:117], v[64:65], 0, v[188:189]
	v_lshlrev_b64 v[64:65], 1, v[116:117]
	v_lshl_add_u64 v[66:67], s[6:7], 0, v[64:65]
	s_waitcnt vmcnt(0) lgkmcnt(0)
	v_fmamk_f32 v68, v68, 0x3a000000, v205
	v_mul_f32_e32 v69, 0x4b800000, v68
	v_cmp_gt_f32_e32 vcc, s40, v68
	v_lshlrev_b32_e32 v140, 16, v128
	s_nop 0
	v_cndmask_b32_e32 v68, v68, v69, vcc
	v_rsq_f32_e32 v70, v68
	v_lshl_add_u64 v[68:69], s[8:9], 0, v[64:65]
	v_lshlrev_b32_e32 v138, 16, v124
	v_and_b32_e32 v139, 0xffff0000, v124
	v_mul_f32_e32 v71, 0x45800000, v70
	v_cndmask_b32_e32 v70, v70, v71, vcc
	v_mul_f32_e32 v143, 0xbfb8aa3b, v70
	v_mul_f32_e32 v62, v62, v143
	v_mul_f32_e32 v63, v63, v143
	v_exp_f32_e32 v62, v62
	v_exp_f32_e32 v63, v63
	v_mul_f32_e32 v56, v56, v143
	v_mul_f32_e32 v57, v57, v143
	v_exp_f32_e32 v56, v56
	v_exp_f32_e32 v57, v57
	v_mul_f32_e32 v58, v58, v143
	v_mul_f32_e32 v59, v59, v143
	v_exp_f32_e32 v58, v58
	v_exp_f32_e32 v59, v59
	v_mul_f32_e32 v52, v52, v143
	v_mul_f32_e32 v53, v53, v143
	v_add_f32_e32 v62, 1.0, v62
	v_add_f32_e32 v63, 1.0, v63
	v_exp_f32_e32 v52, v52
	v_exp_f32_e32 v53, v53
	v_mul_f32_e32 v54, v54, v143
	v_mul_f32_e32 v55, v55, v143
	v_mul_f32_e32 v60, v60, v143
	v_mul_f32_e32 v61, v61, v143
	v_rcp_f32_e32 v62, v62
	v_rcp_f32_e32 v63, v63
	v_add_f32_e32 v56, 1.0, v56
	v_add_f32_e32 v57, 1.0, v57
	v_exp_f32_e32 v54, v54
	v_exp_f32_e32 v55, v55
	v_mul_f32_e32 v48, v48, v143
	v_mul_f32_e32 v49, v49, v143
	v_exp_f32_e32 v60, v60
	v_exp_f32_e32 v61, v61
	v_rcp_f32_e32 v56, v56
	v_rcp_f32_e32 v57, v57
	v_add_f32_e32 v58, 1.0, v58
	v_add_f32_e32 v59, 1.0, v59
	v_exp_f32_e32 v48, v48
	v_exp_f32_e32 v49, v49
	v_rcp_f32_e32 v58, v58
	v_rcp_f32_e32 v59, v59
	v_and_b32_e32 v141, 0xffff0000, v128
	v_lshlrev_b32_e32 v124, 16, v125
	v_and_b32_e32 v125, 0xffff0000, v125
	v_lshlrev_b32_e32 v128, 16, v129
	v_and_b32_e32 v129, 0xffff0000, v129
	v_add_f32_e32 v52, 1.0, v52
	v_add_f32_e32 v53, 1.0, v53
	flat_load_dwordx4 v[72:75], v[66:67] nt
	s_nop 0
; __device__ __forceinline__ float bflo(unsigned u) { return __uint_as_float(u << 16); }
; __device__ __forceinline__ float bfhi(unsigned u) { return __uint_as_float(u & 0xffff0000u); }
;     __device__ __forceinline__ void operator()(const Acc& acc, const Unit& u, int wr, int wc, int fr, int fq) const {
;     ...
;             for (int m = 0; m < 4; ++m) {
;                 const int row = u.pm * 256 + ai * 128 + wr * 64 + m * 16 + fr;
;                 const float rs = rsqrtf(rsv[m] * (1.0f / DM) + EPS) * -1.4426950408889634f;
; #pragma unroll
;                 for (int bj = 0; bj < 2; ++bj) {
;                     const size_t off = (size_t)row * DM + colbase + 32 * bj;
;                     f32x4 h0 = hv[m][bj][0], h1 = hv[m][bj][1];
;                     const u32x4 p4 = pw[m][bj];
;                     const f32x4 a0 = acc[ai][bj][m][0], a1 = acc[ai][bj][m][1];
;                     h0.x += bflo(p4.x) * __builtin_amdgcn_rcpf(1.0f + __builtin_amdgcn_exp2f(a0.x * rs));
;                     h0.y += bfhi(p4.x) * __builtin_amdgcn_rcpf(1.0f + __builtin_amdgcn_exp2f(a0.y * rs));
;                     h0.z += bflo(p4.y) * __builtin_amdgcn_rcpf(1.0f + __builtin_amdgcn_exp2f(a0.z * rs));
;                     h0.w += bfhi(p4.y) * __builtin_amdgcn_rcpf(1.0f + __builtin_amdgcn_exp2f(a0.w * rs));
;                     h1.x += bflo(p4.z) * __builtin_amdgcn_rcpf(1.0f + __builtin_amdgcn_exp2f(a1.x * rs));
;                     h1.y += bfhi(p4.z) * __builtin_amdgcn_rcpf(1.0f + __builtin_amdgcn_exp2f(a1.y * rs));
;                     h1.z += bflo(p4.w) * __builtin_amdgcn_rcpf(1.0f + __builtin_amdgcn_exp2f(a1.z * rs));
;                     h1.w += bfhi(p4.w) * __builtin_amdgcn_rcpf(1.0f + __builtin_amdgcn_exp2f(a1.w * rs));
;                     *(f32x4*)(out + off) = h0; *(f32x4*)(out + off + 4) = h1;
	flat_load_dwordx4 v[64:67], v[66:67] offset:64 nt
	s_nop 0
	flat_load_dwordx4 v[76:79], v[68:69] nt
	s_nop 0
	flat_load_dwordx4 v[68:71], v[68:69] offset:64 nt
	v_pk_fma_f32 v[62:63], v[62:63], v[128:129], v[124:125]
	v_lshlrev_b32_e32 v124, 16, v126
	v_and_b32_e32 v125, 0xffff0000, v126
	v_lshlrev_b32_e32 v128, 16, v130
	v_and_b32_e32 v129, 0xffff0000, v130
	v_rcp_f32_e32 v52, v52
	v_rcp_f32_e32 v53, v53
	v_add_f32_e32 v54, 1.0, v54
	v_add_f32_e32 v55, 1.0, v55
	v_add_f32_e32 v60, 1.0, v60
	v_add_f32_e32 v61, 1.0, v61
	v_pk_fma_f32 v[56:57], v[56:57], v[128:129], v[124:125]
	v_lshlrev_b32_e32 v124, 16, v127
	v_and_b32_e32 v125, 0xffff0000, v127
	v_lshlrev_b32_e32 v126, 16, v131
	v_and_b32_e32 v127, 0xffff0000, v131
	v_rcp_f32_e32 v54, v54
	v_rcp_f32_e32 v55, v55
	v_add_f32_e32 v48, 1.0, v48
	v_add_f32_e32 v49, 1.0, v49
	v_rcp_f32_e32 v60, v60
	v_rcp_f32_e32 v61, v61
	v_pk_fma_f32 v[58:59], v[58:59], v[126:127], v[124:125]
	v_lshl_add_u64 v[124:125], v[136:137], 2, s[2:3]
	v_rcp_f32_e32 v48, v48
	v_rcp_f32_e32 v49, v49
	flat_store_dwordx4 v[124:125], v[56:59] offset:16
	v_pk_fma_f32 v[60:61], v[60:61], v[140:141], v[138:139]
	flat_store_dwordx4 v[124:125], v[60:63]
	v_lshlrev_b32_e32 v56, 16, v132
	v_and_b32_e32 v57, 0xffff0000, v132
	v_lshlrev_b32_e32 v58, 16, v112
	v_and_b32_e32 v59, 0xffff0000, v112
	v_pk_fma_f32 v[52:53], v[52:53], v[58:59], v[56:57]
	v_lshlrev_b32_e32 v56, 16, v133
	v_and_b32_e32 v57, 0xffff0000, v133
	v_lshlrev_b32_e32 v58, 16, v113
	v_and_b32_e32 v59, 0xffff0000, v113
	v_pk_fma_f32 v[54:55], v[54:55], v[58:59], v[56:57]
	v_lshlrev_b32_e32 v56, 16, v134
	v_and_b32_e32 v57, 0xffff0000, v134
	v_lshlrev_b32_e32 v58, 16, v114
	v_and_b32_e32 v59, 0xffff0000, v114
	v_pk_fma_f32 v[48:49], v[48:49], v[58:59], v[56:57]
	v_fmamk_f32 v59, v123, 0x3a000000, v205
	v_mul_f32_e32 v60, 0x4b800000, v59
	v_cmp_gt_f32_e32 vcc, s40, v59
	flat_store_dwordx4 v[124:125], v[52:55] offset:128
	v_mul_f32_e32 v50, v50, v143
	v_cndmask_b32_e32 v59, v59, v60, vcc
	v_rsq_f32_e32 v60, v59
	v_mul_f32_e32 v51, v51, v143
	v_exp_f32_e32 v50, v50
	v_exp_f32_e32 v51, v51
	v_mul_f32_e32 v52, 0x45800000, v60
	v_cndmask_b32_e32 v52, v60, v52, vcc
	v_mul_f32_e32 v52, 0xbfb8aa3b, v52
	v_mul_f32_e32 v44, v44, v52
	v_mul_f32_e32 v45, v45, v52
	v_exp_f32_e32 v44, v44
	v_exp_f32_e32 v45, v45
	v_mul_f32_e32 v46, v46, v52
	v_mul_f32_e32 v47, v47, v52
	v_exp_f32_e32 v46, v46
	v_exp_f32_e32 v47, v47
	v_mul_f32_e32 v40, v40, v52
	v_mul_f32_e32 v41, v41, v52
	v_add_f32_e32 v50, 1.0, v50
	v_add_f32_e32 v51, 1.0, v51
	v_exp_f32_e32 v40, v40
	v_exp_f32_e32 v41, v41
	v_mul_f32_e32 v42, v42, v52
	v_mul_f32_e32 v43, v43, v52
	v_rcp_f32_e32 v50, v50
	v_rcp_f32_e32 v51, v51
	v_exp_f32_e32 v42, v42
	v_exp_f32_e32 v43, v43
	v_add_f32_e32 v44, 1.0, v44
	v_add_f32_e32 v45, 1.0, v45
	v_mul_f32_e32 v36, v36, v52
	v_mul_f32_e32 v37, v37, v52
	v_rcp_f32_e32 v44, v44
	v_rcp_f32_e32 v45, v45
	v_add_f32_e32 v46, 1.0, v46
	v_add_f32_e32 v47, 1.0, v47
	v_exp_f32_e32 v36, v36
	v_exp_f32_e32 v37, v37
	v_mul_f32_e32 v38, v38, v52
	v_mul_f32_e32 v39, v39, v52
	v_lshlrev_b32_e32 v56, 16, v135
	v_and_b32_e32 v57, 0xffff0000, v135
	v_lshlrev_b32_e32 v58, 16, v115
	v_and_b32_e32 v59, 0xffff0000, v115
	v_rcp_f32_e32 v46, v46
	v_rcp_f32_e32 v47, v47
	v_add_f32_e32 v40, 1.0, v40
	v_add_f32_e32 v41, 1.0, v41
	v_exp_f32_e32 v38, v38
	v_exp_f32_e32 v39, v39
	v_mul_f32_e32 v32, v32, v52
	v_mul_f32_e32 v33, v33, v52
	v_pk_fma_f32 v[50:51], v[50:51], v[58:59], v[56:57]
	v_rcp_f32_e32 v40, v40
	v_rcp_f32_e32 v41, v41
	v_add_f32_e32 v42, 1.0, v42
	v_add_f32_e32 v43, 1.0, v43
	v_exp_f32_e32 v32, v32
	v_exp_f32_e32 v33, v33
	flat_store_dwordx4 v[124:125], v[48:51] offset:144
	v_rcp_f32_e32 v42, v42
	v_rcp_f32_e32 v43, v43
	v_lshlrev_b32_e32 v48, 16, v108
	v_and_b32_e32 v49, 0xffff0000, v108
	v_lshlrev_b32_e32 v50, 16, v104
	v_and_b32_e32 v51, 0xffff0000, v104
	v_pk_fma_f32 v[44:45], v[44:45], v[50:51], v[48:49]
	v_lshlrev_b32_e32 v48, 16, v109
	v_and_b32_e32 v49, 0xffff0000, v109
	v_lshlrev_b32_e32 v50, 16, v105
	v_and_b32_e32 v51, 0xffff0000, v105
	v_add_f32_e32 v36, 1.0, v36
	v_add_f32_e32 v37, 1.0, v37
	v_pk_fma_f32 v[46:47], v[46:47], v[50:51], v[48:49]
	v_lshlrev_b32_e32 v48, 16, v110
	v_and_b32_e32 v49, 0xffff0000, v110
	v_lshlrev_b32_e32 v50, 16, v106
	v_and_b32_e32 v51, 0xffff0000, v106
	v_rcp_f32_e32 v36, v36
	v_rcp_f32_e32 v37, v37
	v_add_f32_e32 v38, 1.0, v38
	v_add_f32_e32 v39, 1.0, v39
	v_pk_fma_f32 v[40:41], v[40:41], v[50:51], v[48:49]
	v_lshlrev_b32_e32 v48, 16, v111
	v_and_b32_e32 v49, 0xffff0000, v111
	v_lshlrev_b32_e32 v50, 16, v107
	v_and_b32_e32 v51, 0xffff0000, v107
	v_rcp_f32_e32 v38, v38
	v_rcp_f32_e32 v39, v39
	v_add_f32_e32 v32, 1.0, v32
	v_add_f32_e32 v33, 1.0, v33
	v_pk_fma_f32 v[42:43], v[42:43], v[50:51], v[48:49]
	v_lshl_add_u64 v[48:49], v[120:121], 2, s[2:3]
	v_rcp_f32_e32 v32, v32
	v_rcp_f32_e32 v33, v33
	flat_store_dwordx4 v[48:49], v[40:43] offset:16
	flat_store_dwordx4 v[48:49], v[44:47]
	v_mul_f32_e32 v34, v34, v52
	v_lshlrev_b32_e32 v40, 16, v100
	v_and_b32_e32 v41, 0xffff0000, v100
	v_lshlrev_b32_e32 v42, 16, v96
	v_and_b32_e32 v43, 0xffff0000, v96
	v_pk_fma_f32 v[36:37], v[36:37], v[42:43], v[40:41]
	v_lshlrev_b32_e32 v40, 16, v101
	v_and_b32_e32 v41, 0xffff0000, v101
	v_lshlrev_b32_e32 v42, 16, v97
	v_and_b32_e32 v43, 0xffff0000, v97
	v_pk_fma_f32 v[38:39], v[38:39], v[42:43], v[40:41]
	v_lshlrev_b32_e32 v40, 16, v102
	v_and_b32_e32 v41, 0xffff0000, v102
	v_lshlrev_b32_e32 v42, 16, v98
	v_and_b32_e32 v43, 0xffff0000, v98
	v_pk_fma_f32 v[32:33], v[32:33], v[42:43], v[40:41]
	v_fmamk_f32 v43, v142, 0x3a000000, v205
	v_mul_f32_e32 v44, 0x4b800000, v43
; __device__ __forceinline__ float bflo(unsigned u) { return __uint_as_float(u << 16); }
; __device__ __forceinline__ float bfhi(unsigned u) { return __uint_as_float(u & 0xffff0000u); }
;     __device__ __forceinline__ void operator()(const Acc& acc, const Unit& u, int wr, int wc, int fr, int fq) const {
;     ...
;             for (int m = 0; m < 4; ++m) {
;                 const int row = u.pm * 256 + ai * 128 + wr * 64 + m * 16 + fr;
;                 const float rs = rsqrtf(rsv[m] * (1.0f / DM) + EPS) * -1.4426950408889634f;
; #pragma unroll
;                 for (int bj = 0; bj < 2; ++bj) {
;                     const size_t off = (size_t)row * DM + colbase + 32 * bj;
;                     f32x4 h0 = hv[m][bj][0], h1 = hv[m][bj][1];
;                     const u32x4 p4 = pw[m][bj];
;                     const f32x4 a0 = acc[ai][bj][m][0], a1 = acc[ai][bj][m][1];
;                     h0.x += bflo(p4.x) * __builtin_amdgcn_rcpf(1.0f + __builtin_amdgcn_exp2f(a0.x * rs));
;                     h0.y += bfhi(p4.x) * __builtin_amdgcn_rcpf(1.0f + __builtin_amdgcn_exp2f(a0.y * rs));
;                     h0.z += bflo(p4.y) * __builtin_amdgcn_rcpf(1.0f + __builtin_amdgcn_exp2f(a0.z * rs));
;                     h0.w += bfhi(p4.y) * __builtin_amdgcn_rcpf(1.0f + __builtin_amdgcn_exp2f(a0.w * rs));
;                     h1.x += bflo(p4.z) * __builtin_amdgcn_rcpf(1.0f + __builtin_amdgcn_exp2f(a1.x * rs));
;                     h1.y += bfhi(p4.z) * __builtin_amdgcn_rcpf(1.0f + __builtin_amdgcn_exp2f(a1.y * rs));
;                     h1.z += bflo(p4.w) * __builtin_amdgcn_rcpf(1.0f + __builtin_amdgcn_exp2f(a1.z * rs));
;                     h1.w += bfhi(p4.w) * __builtin_amdgcn_rcpf(1.0f + __builtin_amdgcn_exp2f(a1.w * rs));
;                     *(f32x4*)(out + off) = h0; *(f32x4*)(out + off + 4) = h1;
	v_cmp_gt_f32_e32 vcc, s40, v43
	flat_store_dwordx4 v[48:49], v[36:39] offset:128
	v_mul_f32_e32 v35, v35, v52
	v_cndmask_b32_e32 v43, v43, v44, vcc
	v_rsq_f32_e32 v44, v43
	v_exp_f32_e32 v34, v34
	v_exp_f32_e32 v35, v35
	v_lshlrev_b32_e32 v40, 16, v103
	v_mul_f32_e32 v36, 0x45800000, v44
	v_cndmask_b32_e32 v36, v44, v36, vcc
	v_mul_f32_e32 v36, 0xbfb8aa3b, v36
	v_mul_f32_e32 v28, v28, v36
	v_mul_f32_e32 v29, v29, v36
	v_exp_f32_e32 v28, v28
	v_exp_f32_e32 v29, v29
	v_mul_f32_e32 v30, v30, v36
	v_mul_f32_e32 v31, v31, v36
	v_exp_f32_e32 v30, v30
	v_exp_f32_e32 v31, v31
	v_mul_f32_e32 v24, v24, v36
	v_mul_f32_e32 v25, v25, v36
	v_add_f32_e32 v34, 1.0, v34
	v_add_f32_e32 v35, 1.0, v35
	v_exp_f32_e32 v24, v24
	v_exp_f32_e32 v25, v25
	v_mul_f32_e32 v26, v26, v36
	v_mul_f32_e32 v27, v27, v36
	v_rcp_f32_e32 v34, v34
	v_rcp_f32_e32 v35, v35
	v_exp_f32_e32 v26, v26
	v_exp_f32_e32 v27, v27
	v_add_f32_e32 v28, 1.0, v28
	v_add_f32_e32 v29, 1.0, v29
	v_mul_f32_e32 v20, v20, v36
	v_mul_f32_e32 v21, v21, v36
	v_rcp_f32_e32 v28, v28
	v_rcp_f32_e32 v29, v29
	v_add_f32_e32 v30, 1.0, v30
	v_add_f32_e32 v31, 1.0, v31
	v_exp_f32_e32 v20, v20
	v_exp_f32_e32 v21, v21
	v_mul_f32_e32 v22, v22, v36
	v_mul_f32_e32 v23, v23, v36
	v_and_b32_e32 v41, 0xffff0000, v103
	v_lshlrev_b32_e32 v42, 16, v99
	v_and_b32_e32 v43, 0xffff0000, v99
	v_rcp_f32_e32 v30, v30
	v_rcp_f32_e32 v31, v31
	v_add_f32_e32 v24, 1.0, v24
	v_add_f32_e32 v25, 1.0, v25
	v_exp_f32_e32 v22, v22
	v_exp_f32_e32 v23, v23
	v_mul_f32_e32 v16, v16, v36
	v_mul_f32_e32 v17, v17, v36
	v_pk_fma_f32 v[34:35], v[34:35], v[42:43], v[40:41]
	v_rcp_f32_e32 v24, v24
	v_rcp_f32_e32 v25, v25
	v_add_f32_e32 v26, 1.0, v26
	v_add_f32_e32 v27, 1.0, v27
	v_exp_f32_e32 v16, v16
	v_exp_f32_e32 v17, v17
	flat_store_dwordx4 v[48:49], v[32:35] offset:144
	v_rcp_f32_e32 v26, v26
	v_rcp_f32_e32 v27, v27
	v_lshlrev_b32_e32 v32, 16, v92
	v_and_b32_e32 v33, 0xffff0000, v92
	v_lshlrev_b32_e32 v34, 16, v88
	v_and_b32_e32 v35, 0xffff0000, v88
	v_pk_fma_f32 v[28:29], v[28:29], v[34:35], v[32:33]
	v_lshlrev_b32_e32 v32, 16, v93
	v_and_b32_e32 v33, 0xffff0000, v93
	v_lshlrev_b32_e32 v34, 16, v89
	v_and_b32_e32 v35, 0xffff0000, v89
	v_add_f32_e32 v20, 1.0, v20
	v_add_f32_e32 v21, 1.0, v21
	v_pk_fma_f32 v[30:31], v[30:31], v[34:35], v[32:33]
	v_lshlrev_b32_e32 v32, 16, v94
	v_and_b32_e32 v33, 0xffff0000, v94
	v_lshlrev_b32_e32 v34, 16, v90
	v_and_b32_e32 v35, 0xffff0000, v90
	v_rcp_f32_e32 v20, v20
	v_rcp_f32_e32 v21, v21
	v_add_f32_e32 v22, 1.0, v22
	v_add_f32_e32 v23, 1.0, v23
	v_pk_fma_f32 v[24:25], v[24:25], v[34:35], v[32:33]
	v_lshlrev_b32_e32 v32, 16, v95
	v_and_b32_e32 v33, 0xffff0000, v95
	v_lshlrev_b32_e32 v34, 16, v91
	v_and_b32_e32 v35, 0xffff0000, v91
	v_rcp_f32_e32 v22, v22
	v_rcp_f32_e32 v23, v23
	v_add_f32_e32 v16, 1.0, v16
	v_add_f32_e32 v17, 1.0, v17
	v_pk_fma_f32 v[26:27], v[26:27], v[34:35], v[32:33]
	v_lshl_add_u64 v[32:33], v[118:119], 2, s[2:3]
	v_rcp_f32_e32 v16, v16
	v_rcp_f32_e32 v17, v17
	flat_store_dwordx4 v[32:33], v[24:27] offset:16
	flat_store_dwordx4 v[32:33], v[28:31]
	v_mul_f32_e32 v18, v18, v36
	v_lshlrev_b32_e32 v24, 16, v84
	v_and_b32_e32 v25, 0xffff0000, v84
	v_lshlrev_b32_e32 v26, 16, v80
	v_and_b32_e32 v27, 0xffff0000, v80
	v_pk_fma_f32 v[20:21], v[20:21], v[26:27], v[24:25]
	v_lshlrev_b32_e32 v24, 16, v85
	v_and_b32_e32 v25, 0xffff0000, v85
	v_lshlrev_b32_e32 v26, 16, v81
	v_and_b32_e32 v27, 0xffff0000, v81
	v_pk_fma_f32 v[22:23], v[22:23], v[26:27], v[24:25]
	v_lshlrev_b32_e32 v24, 16, v86
	v_and_b32_e32 v25, 0xffff0000, v86
	v_lshlrev_b32_e32 v26, 16, v82
	v_and_b32_e32 v27, 0xffff0000, v82
	v_pk_fma_f32 v[16:17], v[16:17], v[26:27], v[24:25]
	v_fmamk_f32 v27, v122, 0x3a000000, v205
	v_mul_f32_e32 v28, 0x4b800000, v27
	v_cmp_gt_f32_e32 vcc, s40, v27
	flat_store_dwordx4 v[32:33], v[20:23] offset:128
	v_mul_f32_e32 v19, v19, v36
	v_cndmask_b32_e32 v27, v27, v28, vcc
	v_rsq_f32_e32 v28, v27
	v_exp_f32_e32 v18, v18
	v_exp_f32_e32 v19, v19
	v_lshlrev_b32_e32 v24, 16, v87
	v_mul_f32_e32 v20, 0x45800000, v28
	v_cndmask_b32_e32 v20, v28, v20, vcc
	v_mul_f32_e32 v20, 0xbfb8aa3b, v20
	v_mul_f32_e32 v12, v12, v20
	v_mul_f32_e32 v13, v13, v20
	v_exp_f32_e32 v12, v12
	v_exp_f32_e32 v13, v13
	v_mul_f32_e32 v14, v14, v20
	v_mul_f32_e32 v15, v15, v20
	v_exp_f32_e32 v14, v14
	v_exp_f32_e32 v15, v15
	v_mul_f32_e32 v8, v8, v20
	v_mul_f32_e32 v9, v9, v20
	v_add_f32_e32 v18, 1.0, v18
	v_add_f32_e32 v19, 1.0, v19
	v_exp_f32_e32 v8, v8
	v_exp_f32_e32 v9, v9
	v_mul_f32_e32 v10, v10, v20
	v_mul_f32_e32 v11, v11, v20
	v_rcp_f32_e32 v18, v18
	v_rcp_f32_e32 v19, v19
	v_exp_f32_e32 v10, v10
	v_exp_f32_e32 v11, v11
	v_add_f32_e32 v12, 1.0, v12
	v_add_f32_e32 v13, 1.0, v13
	v_mul_f32_e32 v4, v4, v20
	v_mul_f32_e32 v5, v5, v20
	v_rcp_f32_e32 v12, v12
	v_rcp_f32_e32 v13, v13
	v_add_f32_e32 v14, 1.0, v14
	v_add_f32_e32 v15, 1.0, v15
	v_exp_f32_e32 v4, v4
	v_exp_f32_e32 v5, v5
	v_mul_f32_e32 v6, v6, v20
	v_mul_f32_e32 v7, v7, v20
	v_and_b32_e32 v25, 0xffff0000, v87
	v_lshlrev_b32_e32 v26, 16, v83
	v_and_b32_e32 v27, 0xffff0000, v83
	v_rcp_f32_e32 v14, v14
	v_rcp_f32_e32 v15, v15
	v_add_f32_e32 v8, 1.0, v8
	v_add_f32_e32 v9, 1.0, v9
	v_exp_f32_e32 v6, v6
	v_exp_f32_e32 v7, v7
	v_mul_f32_e32 v0, v0, v20
	v_mul_f32_e32 v1, v1, v20
	v_pk_fma_f32 v[18:19], v[18:19], v[26:27], v[24:25]
	v_rcp_f32_e32 v8, v8
	v_rcp_f32_e32 v9, v9
	v_add_f32_e32 v10, 1.0, v10
	v_add_f32_e32 v11, 1.0, v11
	v_exp_f32_e32 v0, v0
	v_exp_f32_e32 v1, v1
	v_mul_f32_e32 v2, v2, v20
	v_mul_f32_e32 v3, v3, v20
	flat_store_dwordx4 v[32:33], v[16:19] offset:144
	v_rcp_f32_e32 v10, v10
	v_rcp_f32_e32 v11, v11
	s_waitcnt vmcnt(0) lgkmcnt(0)
; __device__ __forceinline__ float bflo(unsigned u) { return __uint_as_float(u << 16); }
; #define PG8_BAR __builtin_amdgcn_s_barrier()
; template <class Epi, bool ALIGN_EPI>
; __device__ __forceinline__ void gemm_phase(LAS unsigned char* lds, const Gemm g, const StaticOrder& S, const Epi& E, const int wid) {
;     ...
;         if (!has_next) break;
; #pragma unroll
;         for (int a = 0; a < 2; ++a)
; #pragma unroll
;             for (int b = 0; b < 2; ++b)
; #pragma unroll
;                 for (int m = 0; m < 4; ++m)
; #pragma unroll
;                     for (int n = 0; n < 2; ++n) acc[a][b][m][n] = (f32x4){0.f, 0.f, 0.f, 0.f};
;         cur = nxt; cA = nA; cB = nB; ++ui;
;         if constexpr (ALIGN_EPI) { if (wr == 1) PG8_BAR; }
;     __device__ __forceinline__ void operator()(const Acc& acc, const Unit& u, int wr, int wc, int fr, int fq) const {
;     ...
;             for (int m = 0; m < 4; ++m) {
;                 const int row = u.pm * 256 + ai * 128 + wr * 64 + m * 16 + fr;
;                 const float rs = rsqrtf(rsv[m] * (1.0f / DM) + EPS) * -1.4426950408889634f;
; #pragma unroll
;                 for (int bj = 0; bj < 2; ++bj) {
;                     const size_t off = (size_t)row * DM + colbase + 32 * bj;
;                     f32x4 h0 = hv[m][bj][0], h1 = hv[m][bj][1];
;                     const u32x4 p4 = pw[m][bj];
;                     const f32x4 a0 = acc[ai][bj][m][0], a1 = acc[ai][bj][m][1];
;                     h0.x += bflo(p4.x) * __builtin_amdgcn_rcpf(1.0f + __builtin_amdgcn_exp2f(a0.x * rs));
;                     h0.y += bfhi(p4.x) * __builtin_amdgcn_rcpf(1.0f + __builtin_amdgcn_exp2f(a0.y * rs));
;                     h0.z += bflo(p4.y) * __builtin_amdgcn_rcpf(1.0f + __builtin_amdgcn_exp2f(a0.z * rs));
;                     h0.w += bfhi(p4.y) * __builtin_amdgcn_rcpf(1.0f + __builtin_amdgcn_exp2f(a0.w * rs));
;                     h1.x += bflo(p4.z) * __builtin_amdgcn_rcpf(1.0f + __builtin_amdgcn_exp2f(a1.x * rs));
;                     h1.y += bfhi(p4.z) * __builtin_amdgcn_rcpf(1.0f + __builtin_amdgcn_exp2f(a1.y * rs));
;                     h1.z += bflo(p4.w) * __builtin_amdgcn_rcpf(1.0f + __builtin_amdgcn_exp2f(a1.z * rs));
;                     h1.w += bfhi(p4.w) * __builtin_amdgcn_rcpf(1.0f + __builtin_amdgcn_exp2f(a1.w * rs));
;                     *(f32x4*)(out + off) = h0; *(f32x4*)(out + off + 4) = h1;
	v_lshlrev_b32_e32 v16, 16, v72
	v_and_b32_e32 v17, 0xffff0000, v72
	v_lshlrev_b32_e32 v18, 16, v76
	v_and_b32_e32 v19, 0xffff0000, v76
	v_exp_f32_e32 v2, v2
	v_exp_f32_e32 v3, v3
	v_pk_fma_f32 v[12:13], v[12:13], v[18:19], v[16:17]
	v_lshlrev_b32_e32 v16, 16, v73
	v_and_b32_e32 v17, 0xffff0000, v73
	v_lshlrev_b32_e32 v18, 16, v77
	v_and_b32_e32 v19, 0xffff0000, v77
	v_add_f32_e32 v4, 1.0, v4
	v_add_f32_e32 v5, 1.0, v5
	v_pk_fma_f32 v[14:15], v[14:15], v[18:19], v[16:17]
	v_lshlrev_b32_e32 v16, 16, v74
	v_and_b32_e32 v17, 0xffff0000, v74
	v_lshlrev_b32_e32 v18, 16, v78
	v_and_b32_e32 v19, 0xffff0000, v78
	v_rcp_f32_e32 v4, v4
	v_rcp_f32_e32 v5, v5
	v_add_f32_e32 v6, 1.0, v6
	v_add_f32_e32 v7, 1.0, v7
	v_pk_fma_f32 v[8:9], v[8:9], v[18:19], v[16:17]
	v_lshlrev_b32_e32 v16, 16, v75
	v_and_b32_e32 v17, 0xffff0000, v75
	v_lshlrev_b32_e32 v18, 16, v79
	v_and_b32_e32 v19, 0xffff0000, v79
	v_rcp_f32_e32 v6, v6
	v_rcp_f32_e32 v7, v7
	v_add_f32_e32 v0, 1.0, v0
	v_add_f32_e32 v1, 1.0, v1
	v_pk_fma_f32 v[10:11], v[10:11], v[18:19], v[16:17]
	v_lshl_add_u64 v[16:17], v[116:117], 2, s[2:3]
	v_rcp_f32_e32 v0, v0
	v_rcp_f32_e32 v1, v1
	v_add_f32_e32 v2, 1.0, v2
	v_add_f32_e32 v3, 1.0, v3
	flat_store_dwordx4 v[16:17], v[8:11] offset:16
	v_rcp_f32_e32 v2, v2
	v_rcp_f32_e32 v3, v3
	v_lshlrev_b32_e32 v8, 16, v64
	v_and_b32_e32 v9, 0xffff0000, v64
	v_lshlrev_b32_e32 v10, 16, v68
	v_and_b32_e32 v11, 0xffff0000, v68
	v_pk_fma_f32 v[4:5], v[4:5], v[10:11], v[8:9]
	v_lshlrev_b32_e32 v8, 16, v65
	v_and_b32_e32 v9, 0xffff0000, v65
	v_lshlrev_b32_e32 v10, 16, v69
	v_and_b32_e32 v11, 0xffff0000, v69
	v_pk_fma_f32 v[6:7], v[6:7], v[10:11], v[8:9]
	v_lshlrev_b32_e32 v8, 16, v66
	v_and_b32_e32 v9, 0xffff0000, v66
	v_lshlrev_b32_e32 v10, 16, v70
	v_and_b32_e32 v11, 0xffff0000, v70
	v_pk_fma_f32 v[0:1], v[0:1], v[10:11], v[8:9]
	v_lshlrev_b32_e32 v8, 16, v67
	v_and_b32_e32 v9, 0xffff0000, v67
	v_lshlrev_b32_e32 v10, 16, v71
	v_and_b32_e32 v11, 0xffff0000, v71
	s_andn2_b64 vcc, exec, s[4:5]
	s_mov_b64 s[4:5], -1
	flat_store_dwordx4 v[16:17], v[12:15]
	v_pk_fma_f32 v[2:3], v[2:3], v[10:11], v[8:9]
	flat_store_dwordx4 v[16:17], v[4:7] offset:128
	flat_store_dwordx4 v[16:17], v[0:3] offset:144
	s_cbranch_vccnz .LBB0_803
	s_and_b64 vcc, exec, s[0:1]
	s_cbranch_vccnz .LBB0_802
	s_barrier
	s_branch .LBB0_802
